# grid barriers: waiting workgroups also poll the top-level generation word and leave as soon as it advances (one release hop less)
# baseline (speedup 1.0000x reference)
.LBB0_202:
	s_or_b64 exec, exec, s[8:9]
	v_cvt_f32_u32_e32 v4, v2
	s_waitcnt vmcnt(0)
	v_readfirstlane_b32 s3, v3
	v_sub_u32_e32 v3, 0, v2
	v_rcp_iflag_f32_e32 v4, v4
	v_add_u32_e32 v5, s3, v1
	v_mul_f32_e32 v4, 0x4f7ffffe, v4
	v_cvt_u32_f32_e32 v4, v4
	v_mul_lo_u32 v1, v3, v4
	v_mul_hi_u32 v1, v4, v1
	v_add_u32_e32 v1, v4, v1
	v_mul_hi_u32 v1, v5, v1
	v_mul_lo_u32 v3, v1, v2
	v_sub_u32_e32 v3, v5, v3
	v_add_u32_e32 v4, 1, v1
	v_cmp_ge_u32_e32 vcc, v3, v2
	s_nop 1
	v_cndmask_b32_e32 v1, v1, v4, vcc
	v_sub_u32_e32 v4, v3, v2
	v_cndmask_b32_e32 v3, v3, v4, vcc
	v_add_u32_e32 v4, 1, v1
	v_cmp_ge_u32_e32 vcc, v3, v2
	v_add_u32_e32 v3, 1, v5
	s_nop 0
	v_cndmask_b32_e32 v1, v1, v4, vcc
	v_mul_lo_u32 v4, v2, v1
	v_add_u32_e32 v2, v4, v2
	v_cmp_ne_u32_e32 vcc, v3, v2
	s_and_saveexec_b64 s[6:7], vcc
	s_xor_b64 s[6:7], exec, s[6:7]
	s_cbranch_execz .LBB0_216
	s_waitcnt lgkmcnt(0)
	v_mov_b32_e32 v0, 0x2000
	global_load_dword v0, v0, s[4:5] offset:1024 sc1
	s_add_u32 s14, s4, 0x2400
	s_addc_u32 s15, s5, 0
	s_waitcnt vmcnt(0)
	v_cmp_eq_u32_e32 vcc, v0, v1
	s_and_saveexec_b64 s[8:9], vcc
	s_cbranch_execz .LBB0_215
	s_add_u32 s60, s72, 0x5c3500
	s_addc_u32 s61, s73, 0
	s_add_u32 s10, s72, 0x5c0200
	s_addc_u32 s11, s73, 0
	s_mov_b32 s3, 1
	s_mov_b64 s[18:19], 0
	v_mov_b32_e32 v0, 0
	s_branch .LBB0_206

.LBB0_208:
	global_load_dword v2, v0, s[14:15] sc1
	global_load_dword v3, v0, s[60:61] sc1
	s_add_i32 s3, s3, 1
	s_mov_b64 s[24:25], -1
	s_waitcnt vmcnt(0)
	v_cmp_ne_u32_e32 vcc, v2, v1
	v_cmp_le_u32_e64 s[62:63], 2, v3
	s_cmp_lg_u32 s98, 0
	s_cselect_b64 s[62:63], s[62:63], 0
	s_or_b64 vcc, vcc, s[62:63]
	s_orn2_b64 s[22:23], vcc, exec
	s_branch .LBB0_205

.LBB0_430:
	s_or_b64 exec, exec, s[8:9]
	v_cvt_f32_u32_e32 v4, v2
	s_waitcnt vmcnt(0)
	v_readfirstlane_b32 s3, v3
	v_sub_u32_e32 v3, 0, v2
	v_rcp_iflag_f32_e32 v4, v4
	v_add_u32_e32 v5, s3, v1
	v_mul_f32_e32 v4, 0x4f7ffffe, v4
	v_cvt_u32_f32_e32 v4, v4
	v_mul_lo_u32 v1, v3, v4
	v_mul_hi_u32 v1, v4, v1
	v_add_u32_e32 v1, v4, v1
	v_mul_hi_u32 v1, v5, v1
	v_mul_lo_u32 v3, v1, v2
	v_sub_u32_e32 v3, v5, v3
	v_add_u32_e32 v4, 1, v1
	v_cmp_ge_u32_e32 vcc, v3, v2
	s_nop 1
	v_cndmask_b32_e32 v1, v1, v4, vcc
	v_sub_u32_e32 v4, v3, v2
	v_cndmask_b32_e32 v3, v3, v4, vcc
	v_add_u32_e32 v4, 1, v1
	v_cmp_ge_u32_e32 vcc, v3, v2
	v_add_u32_e32 v3, 1, v5
	s_nop 0
	v_cndmask_b32_e32 v1, v1, v4, vcc
	v_mul_lo_u32 v4, v2, v1
	v_add_u32_e32 v2, v4, v2
	v_cmp_ne_u32_e32 vcc, v3, v2
	s_and_saveexec_b64 s[6:7], vcc
	s_xor_b64 s[6:7], exec, s[6:7]
	s_cbranch_execz .LBB0_444
	s_waitcnt lgkmcnt(0)
	v_mov_b32_e32 v0, 0x2000
	global_load_dword v0, v0, s[4:5] offset:1024 sc1
	s_add_u32 s14, s4, 0x2400
	s_addc_u32 s15, s5, 0
	s_waitcnt vmcnt(0)
	v_cmp_eq_u32_e32 vcc, v0, v1
	s_and_saveexec_b64 s[8:9], vcc
	s_cbranch_execz .LBB0_443
	s_add_u32 s60, s72, 0x5c3500
	s_addc_u32 s61, s73, 0
	s_add_u32 s10, s72, 0x5c0200
	s_addc_u32 s11, s73, 0
	s_mov_b32 s3, 1
	s_mov_b64 s[16:17], 0
	v_mov_b32_e32 v0, 0
	s_branch .LBB0_434

.LBB0_436:
	global_load_dword v2, v0, s[14:15] sc1
	global_load_dword v3, v0, s[60:61] sc1
	s_add_i32 s3, s3, 1
	s_mov_b64 s[38:39], -1
	s_waitcnt vmcnt(0)
	v_cmp_ne_u32_e32 vcc, v2, v1
	v_cmp_le_u32_e64 s[62:63], 3, v3
	s_cmp_lg_u32 s98, 0
	s_cselect_b64 s[62:63], s[62:63], 0
	s_or_b64 vcc, vcc, s[62:63]
	s_orn2_b64 s[30:31], vcc, exec
	s_branch .LBB0_433

.LBB0_721:
	global_load_dword v2, v0, s[14:15] sc1
	global_load_dword v3, v0, s[60:61] sc1
	s_add_i32 s3, s3, 1
	s_mov_b64 s[42:43], -1
	s_waitcnt vmcnt(0)
	v_cmp_ne_u32_e32 vcc, v2, v1
	v_cmp_le_u32_e64 s[62:63], 4, v3
	s_cmp_lg_u32 s98, 0
	s_cselect_b64 s[62:63], s[62:63], 0
	s_or_b64 vcc, vcc, s[62:63]
	s_orn2_b64 s[40:41], vcc, exec
	s_branch .LBB0_718

.LBB0_894:
	s_or_b64 exec, exec, s[14:15]
	v_cvt_f32_u32_e32 v4, v2
	s_waitcnt vmcnt(0)
	v_readfirstlane_b32 s10, v3
	v_sub_u32_e32 v3, 0, v2
	v_rcp_iflag_f32_e32 v4, v4
	v_add_u32_e32 v5, s10, v1
	v_mul_f32_e32 v4, 0x4f7ffffe, v4
	v_cvt_u32_f32_e32 v4, v4
	v_mul_lo_u32 v1, v3, v4
	v_mul_hi_u32 v1, v4, v1
	v_add_u32_e32 v1, v4, v1
	v_mul_hi_u32 v1, v5, v1
	v_mul_lo_u32 v3, v1, v2
	v_sub_u32_e32 v3, v5, v3
	v_add_u32_e32 v4, 1, v1
	v_cmp_ge_u32_e32 vcc, v3, v2
	s_nop 1
	v_cndmask_b32_e32 v1, v1, v4, vcc
	v_sub_u32_e32 v4, v3, v2
	v_cndmask_b32_e32 v3, v3, v4, vcc
	v_add_u32_e32 v4, 1, v1
	v_cmp_ge_u32_e32 vcc, v3, v2
	v_add_u32_e32 v3, 1, v5
	s_nop 0
	v_cndmask_b32_e32 v1, v1, v4, vcc
	v_mul_lo_u32 v4, v2, v1
	v_add_u32_e32 v2, v4, v2
	v_cmp_ne_u32_e32 vcc, v3, v2
	s_and_saveexec_b64 s[10:11], vcc
	s_xor_b64 s[10:11], exec, s[10:11]
	s_cbranch_execz .LBB0_908
	s_waitcnt lgkmcnt(0)
	v_mov_b32_e32 v0, 0x2000
	global_load_dword v0, v0, s[6:7] offset:1024 sc1
	s_add_u32 s18, s6, 0x2400
	s_addc_u32 s19, s7, 0
	s_waitcnt vmcnt(0)
	v_cmp_eq_u32_e32 vcc, v0, v1
	s_and_saveexec_b64 s[14:15], vcc
	s_cbranch_execz .LBB0_907
	s_add_u32 s60, s72, 0x5c3500
	s_addc_u32 s61, s73, 0
	s_add_u32 s16, s72, 0x5c0200
	s_addc_u32 s17, s73, 0
	s_mov_b32 s12, 1
	s_mov_b64 s[42:43], 0
	v_mov_b32_e32 v0, 0
	s_branch .LBB0_898

.LBB0_900:
	global_load_dword v2, v0, s[18:19] sc1
	global_load_dword v3, v0, s[60:61] sc1
	s_add_i32 s12, s12, 1
	s_mov_b64 s[52:53], -1
	s_waitcnt vmcnt(0)
	v_cmp_ne_u32_e32 vcc, v2, v1
	v_cmp_le_u32_e64 s[62:63], 5, v3
	s_cmp_lg_u32 s98, 0
	s_cselect_b64 s[62:63], s[62:63], 0
	s_or_b64 vcc, vcc, s[62:63]
	s_orn2_b64 s[50:51], vcc, exec
	s_branch .LBB0_897

.LBB0_978:
	s_or_b64 exec, exec, s[14:15]
	v_cvt_f32_u32_e32 v4, v2
	s_waitcnt vmcnt(0)
	v_readfirstlane_b32 s3, v3
	v_sub_u32_e32 v3, 0, v2
	v_rcp_iflag_f32_e32 v4, v4
	v_add_u32_e32 v5, s3, v1
	v_mul_f32_e32 v4, 0x4f7ffffe, v4
	v_cvt_u32_f32_e32 v4, v4
	v_mul_lo_u32 v1, v3, v4
	v_mul_hi_u32 v1, v4, v1
	v_add_u32_e32 v1, v4, v1
	v_mul_hi_u32 v1, v5, v1
	v_mul_lo_u32 v3, v1, v2
	v_sub_u32_e32 v3, v5, v3
	v_add_u32_e32 v4, 1, v1
	v_cmp_ge_u32_e32 vcc, v3, v2
	s_nop 1
	v_cndmask_b32_e32 v1, v1, v4, vcc
	v_sub_u32_e32 v4, v3, v2
	v_cndmask_b32_e32 v3, v3, v4, vcc
	v_add_u32_e32 v4, 1, v1
	v_cmp_ge_u32_e32 vcc, v3, v2
	v_add_u32_e32 v3, 1, v5
	s_nop 0
	v_cndmask_b32_e32 v1, v1, v4, vcc
	v_mul_lo_u32 v4, v2, v1
	v_add_u32_e32 v2, v4, v2
	v_cmp_ne_u32_e32 vcc, v3, v2
	s_and_saveexec_b64 s[10:11], vcc
	s_xor_b64 s[10:11], exec, s[10:11]
	s_cbranch_execz .LBB0_992
	s_waitcnt lgkmcnt(0)
	v_mov_b32_e32 v0, 0x2000
	global_load_dword v0, v0, s[4:5] offset:1024 sc1
	s_add_u32 s18, s4, 0x2400
	s_addc_u32 s19, s5, 0
	s_waitcnt vmcnt(0)
	v_cmp_eq_u32_e32 vcc, v0, v1
	s_and_saveexec_b64 s[14:15], vcc
	s_cbranch_execz .LBB0_991
	s_add_u32 s60, s72, 0x5c3500
	s_addc_u32 s61, s73, 0
	s_add_u32 s16, s72, 0x5c0200
	s_addc_u32 s17, s73, 0
	s_mov_b32 s3, 1
	s_mov_b64 s[36:37], 0
	v_mov_b32_e32 v0, 0
	s_branch .LBB0_982

.LBB0_984:
	global_load_dword v2, v0, s[18:19] sc1
	global_load_dword v3, v0, s[60:61] sc1
	s_add_i32 s3, s3, 1
	s_mov_b64 s[42:43], -1
	s_waitcnt vmcnt(0)
	v_cmp_ne_u32_e32 vcc, v2, v1
	v_cmp_le_u32_e64 s[62:63], 6, v3
	s_cmp_lg_u32 s98, 0
	s_cselect_b64 s[62:63], s[62:63], 0
	s_or_b64 vcc, vcc, s[62:63]
	s_orn2_b64 s[40:41], vcc, exec
	s_branch .LBB0_981
